# S5 prompt scan rewritten: tokens split 0-15/16-31 across half-waves, permlane32 hand-offs, in-place packed recurrence, cvt_pk bf16 for LDS staging
# speedup vs baseline: 1.1680x; 1.0221x over previous
; #define LAS __attribute__((address_space(3)))
; template <bool OUT>
; DI void s5_tile(const S5C& K, const float* U, int row0, int g, int nruns, int nvalid, float (&hre)[2], float (&him)[2], LAS bf16_t* Hs, const float* dvec, bf16_t* YC0, int lane) {
;     const int tok = lane & 31, half = lane >> 5;
;     bf16x8 af = {0, 0, 0, 0, 0, 0, 0, 0};
;     if (tok < nvalid) { const float* up = U + (size_t)(row0 + tok) * 512 + g * 16 + half * 8; af = pack8(*(const f32x4*)up, *(const f32x4*)(up + 4)); }
;     f32x16 z16;
; #pragma unroll
;     for (int i = 0; i < 16; ++i) z16[i] = 0.f;
;     f32x16 dre[2], dim[2];
; #pragma unroll
;     for (int st = 0; st < 2; ++st) { dre[st] = MFMA32(af, K.bbf[st], z16); dim[st] = MFMA32(af, K.bbf[2 + st], z16); }
; #pragma unroll
;     for (int r = 0; r < 8; ++r) {
;         if (r < nruns) {
;             const int hf = r & 1, i0 = 4 * (r >> 1);
;             if (half == hf) {
; #pragma unroll
;                 for (int k = 0; k < 4; ++k)
; #pragma unroll
;                     for (int st = 0; st < 2; ++st) { const float nr = K.are[st] * hre[st] - K.aim[st] * him[st] + dre[st][i0 + k]; const float ni = K.are[st] * him[st] + K.aim[st] * hre[st] + dim[st][i0 + k];
;                         hre[st] = nr; him[st] = ni; dre[st][i0 + k] = nr; dim[st][i0 + k] = ni; }
;             }
; #pragma unroll
;             for (int st = 0; st < 2; ++st) { const float pr = __shfl_xor(hre[st], 32), pi = __shfl_xor(him[st], 32); if (half != hf) { hre[st] = pr; him[st] = pi; } }
;         }
;     }
; DI void s5_load_consts(S5C& K, const unsigned char* ws, int lg, int lane) {
;     const bf16_t* BBF = (const bf16_t*)(ws + WS_TAB + TB_BBF); const bf16_t* CF = (const bf16_t*)(ws + WS_TAB + TB_CF); const float* AB = (const float*)(ws + WS_TAB + TB_ABAR);
; #pragma unroll
;     for (int t = 0; t < 4; ++t) { K.bbf[t] = *(const bf16x8*)(BBF + (((size_t)lg * 4 + t) * 64 + lane) * 8); K.cf[t] = *(const bf16x8*)(CF + (((size_t)lg * 4 + t) * 64 + lane) * 8); }
; #pragma unroll
;     for (int st = 0; st < 2; ++st) { const int p = st * 32 + (lane & 31); K.are[st] = AB[((size_t)lg * 64 + p) * 2]; K.aim[st] = AB[((size_t)lg * 64 + p) * 2 + 1]; }
; }
; DI void s5_prompt_task(LAS unsigned char* lds, int task, int l, ArgsP a, const float* U, bf16_t* YC0, int tid) {
;     const int b = task >> 5, g = task & 31, lg = l * 32 + g, wave = tid >> 6, lane = tid & 63;
.LBB0_900:
	s_and_b32 s42, s39, 31
	s_or_b32 s14, s42, s33
	s_ashr_i32 s15, s14, 31
	s_lshl_b64 s[30:31], s[14:15], 12
	v_lshl_or_b32 v0, v170, 1, s30
	v_mov_b32_e32 v1, s31
	v_lshl_add_u64 v[2:3], s[18:19], 0, v[0:1]
	s_ashr_i32 s43, s39, 5
	v_lshl_add_u64 v[4:5], s[20:21], 0, v[0:1]
	global_load_dwordx4 v[98:101], v[2:3], off
	global_load_dwordx4 v[102:105], v[4:5], off
	v_mov_b32_e32 v3, s31
	s_lshl_b64 s[30:31], s[14:15], 9
	v_or_b32_e32 v2, 0x400, v0
	s_add_u32 s14, s22, s30
	v_lshl_add_u64 v[4:5], s[18:19], 0, v[2:3]
	s_addc_u32 s15, s23, s31
	v_lshlrev_b32_e32 v6, 2, v171
	v_lshl_add_u64 v[2:3], s[20:21], 0, v[2:3]
	global_load_dwordx2 v[144:145], v6, s[14:15]
	global_load_dwordx2 v[150:151], v134, s[14:15]
	global_load_dwordx4 v[106:109], v[4:5], off
	global_load_dwordx4 v[110:113], v[2:3], off
	v_or_b32_e32 v2, 0x800, v0
	v_mov_b32_e32 v3, v1
	v_lshl_add_u64 v[4:5], s[18:19], 0, v[2:3]
	v_lshl_add_u64 v[2:3], s[20:21], 0, v[2:3]
	v_or_b32_e32 v0, 0xc00, v0
	global_load_dwordx4 v[114:117], v[4:5], off
	global_load_dwordx4 v[118:121], v[2:3], off
	v_lshl_add_u64 v[2:3], s[18:19], 0, v[0:1]
	v_lshl_add_u64 v[0:1], s[20:21], 0, v[0:1]
	global_load_dwordx4 v[122:125], v[2:3], off
	global_load_dwordx4 v[126:129], v[0:1], off
	s_lshl_b32 s45, s42, 4
	s_lshl_b32 s44, s43, 11
	s_lshl_b32 s14, s42, 6
	s_add_u32 s14, s4, s14
	v_mov_b32_e32 v143, v97
	v_mov_b32_e32 v96, v97
	v_add_u32_e32 v0, s44, v135
	s_addc_u32 s15, s5, 0
	s_mov_b32 s52, 0
	v_mov_b64_e32 v[78:79], v[96:97]
	v_and_b32_e32 v90, 4, v132
	v_lshrrev_b32_e32 v91, 1, v132
	v_lshlrev_b32_e32 v90, 2, v90
	v_and_b32_e32 v91, 12, v91
	v_and_b32_e32 v92, 3, v132
	v_or3_b32 v90, v90, v91, v92
	v_or_b32_e32 v179, v0, v90
	v_lshl_add_u64 v[64:65], s[14:15], 0, v[142:143]
	v_mov_b64_e32 v[80:81], v[96:97]
	s_movk_i32 s40, 0xcc0
	v_lshrrev_b32_e32 v91, 3, v172
	v_mad_u32_u24 v90, v91, s40, v173
	s_waitcnt vmcnt(0)
	v_pk_mov_b32 v[152:153], v[144:145], v[144:145] op_sel:[1,0]
	v_pk_mov_b32 v[154:155], v[150:151], v[150:151] op_sel:[1,0]
	v_mov_b64_e32 v[66:67], v[96:97]
	v_mov_b64_e32 v[68:69], v[96:97]
	v_ashrrev_i32_e32 v1, 31, v179
	v_mov_b32_e32 v0, v179
	v_lshlrev_b64 v[0:1], 11, v[0:1]
	v_lshl_add_u64 v[4:5], v[64:65], 0, v[0:1]
	global_load_dwordx4 v[198:201], v[4:5], off
	global_load_dwordx4 v[202:205], v[4:5], off offset:16
.Ls5a_tile:
	s_waitcnt vmcnt(0)
	v_cvt_pk_bf16_f32 v86, v198, v199
	v_cvt_pk_bf16_f32 v87, v200, v201
	v_cvt_pk_bf16_f32 v88, v202, v203
	v_cvt_pk_bf16_f32 v89, v204, v205
	v_add_u32_e32 v92, s52, v179
	v_add_u32_e32 v92, 32, v92
	v_mfma_f32_32x32x16_bf16 v[0:15], v[86:89], v[98:101], 0
	v_mfma_f32_32x32x16_bf16 v[32:47], v[86:89], v[114:117], 0
	v_mfma_f32_32x32x16_bf16 v[16:31], v[86:89], v[106:109], 0
	v_mfma_f32_32x32x16_bf16 v[48:63], v[86:89], v[122:125], 0
	v_ashrrev_i32_e32 v93, 31, v92
	v_lshlrev_b64 v[92:93], 11, v[92:93]
	v_lshl_add_u64 v[92:93], v[64:65], 0, v[92:93]
	global_load_dwordx4 v[198:201], v[92:93], off
	global_load_dwordx4 v[202:205], v[92:93], off offset:16
	s_mov_b64 exec, s[6:7]
	v_pk_mul_f32 v[70:71], v[152:153], v[66:67] op_sel:[0,1]
	v_pk_mul_f32 v[74:75], v[154:155], v[68:69] op_sel:[0,1]
	v_pk_fma_f32 v[72:73], v[144:145], v[66:67], v[70:71] op_sel_hi:[1,0,1] neg_lo:[0,0,1]
	v_pk_fma_f32 v[76:77], v[150:151], v[68:69], v[74:75] op_sel_hi:[1,0,1] neg_lo:[0,0,1]
	v_add_f32_e32 v0, v72, v0
	v_add_f32_e32 v32, v73, v32
	v_add_f32_e32 v16, v76, v16
	v_add_f32_e32 v48, v77, v48
	v_pk_mul_f32 v[70:71], v[152:153], v[32:33] op_sel_hi:[1,0]
	v_pk_mul_f32 v[74:75], v[154:155], v[48:49] op_sel_hi:[1,0]
	v_pk_fma_f32 v[72:73], v[144:145], v[0:1], v[70:71] op_sel_hi:[1,0,1] neg_lo:[0,0,1]
	v_pk_fma_f32 v[76:77], v[150:151], v[16:17], v[74:75] op_sel_hi:[1,0,1] neg_lo:[0,0,1]
	v_add_f32_e32 v1, v72, v1
	v_add_f32_e32 v33, v73, v33
	v_add_f32_e32 v17, v76, v17
	v_add_f32_e32 v49, v77, v49
	v_pk_mul_f32 v[70:71], v[152:153], v[32:33] op_sel:[0,1]
	v_pk_mul_f32 v[74:75], v[154:155], v[48:49] op_sel:[0,1]
	v_pk_fma_f32 v[72:73], v[144:145], v[0:1], v[70:71] op_sel:[0,1,0] neg_lo:[0,0,1]
	v_pk_fma_f32 v[76:77], v[150:151], v[16:17], v[74:75] op_sel:[0,1,0] neg_lo:[0,0,1]
	v_add_f32_e32 v2, v72, v2
	v_add_f32_e32 v34, v73, v34
	v_add_f32_e32 v18, v76, v18
	v_add_f32_e32 v50, v77, v50
	v_pk_mul_f32 v[70:71], v[152:153], v[34:35] op_sel_hi:[1,0]
	v_pk_mul_f32 v[74:75], v[154:155], v[50:51] op_sel_hi:[1,0]
	v_pk_fma_f32 v[72:73], v[144:145], v[2:3], v[70:71] op_sel_hi:[1,0,1] neg_lo:[0,0,1]
	v_pk_fma_f32 v[76:77], v[150:151], v[18:19], v[74:75] op_sel_hi:[1,0,1] neg_lo:[0,0,1]
	v_add_f32_e32 v3, v72, v3
	v_add_f32_e32 v35, v73, v35
	v_add_f32_e32 v19, v76, v19
	v_add_f32_e32 v51, v77, v51
	v_pk_mul_f32 v[70:71], v[152:153], v[34:35] op_sel:[0,1]
	v_pk_mul_f32 v[74:75], v[154:155], v[50:51] op_sel:[0,1]
	v_pk_fma_f32 v[72:73], v[144:145], v[2:3], v[70:71] op_sel:[0,1,0] neg_lo:[0,0,1]
	v_pk_fma_f32 v[76:77], v[150:151], v[18:19], v[74:75] op_sel:[0,1,0] neg_lo:[0,0,1]
	v_add_f32_e32 v4, v72, v4
	v_add_f32_e32 v36, v73, v36
	v_add_f32_e32 v20, v76, v20
	v_add_f32_e32 v52, v77, v52
	v_pk_mul_f32 v[70:71], v[152:153], v[36:37] op_sel_hi:[1,0]
	v_pk_mul_f32 v[74:75], v[154:155], v[52:53] op_sel_hi:[1,0]
	v_pk_fma_f32 v[72:73], v[144:145], v[4:5], v[70:71] op_sel_hi:[1,0,1] neg_lo:[0,0,1]
	v_pk_fma_f32 v[76:77], v[150:151], v[20:21], v[74:75] op_sel_hi:[1,0,1] neg_lo:[0,0,1]
	v_add_f32_e32 v5, v72, v5
	v_add_f32_e32 v37, v73, v37
	v_add_f32_e32 v21, v76, v21
	v_add_f32_e32 v53, v77, v53
	v_pk_mul_f32 v[70:71], v[152:153], v[36:37] op_sel:[0,1]
	v_pk_mul_f32 v[74:75], v[154:155], v[52:53] op_sel:[0,1]
	v_pk_fma_f32 v[72:73], v[144:145], v[4:5], v[70:71] op_sel:[0,1,0] neg_lo:[0,0,1]
; template <bool OUT>
; DI void s5_tile(const S5C& K, const float* U, int row0, int g, int nruns, int nvalid, float (&hre)[2], float (&him)[2], LAS bf16_t* Hs, const float* dvec, bf16_t* YC0, int lane) {
;     ...
;     for (int r = 0; r < 8; ++r) {
;         if (r < nruns) {
;             const int hf = r & 1, i0 = 4 * (r >> 1);
;             if (half == hf) {
; #pragma unroll
;                 for (int k = 0; k < 4; ++k)
; #pragma unroll
;                     for (int st = 0; st < 2; ++st) { const float nr = K.are[st] * hre[st] - K.aim[st] * him[st] + dre[st][i0 + k]; const float ni = K.are[st] * him[st] + K.aim[st] * hre[st] + dim[st][i0 + k];
;                         hre[st] = nr; him[st] = ni; dre[st][i0 + k] = nr; dim[st][i0 + k] = ni; }
;             }
; #pragma unroll
;             for (int st = 0; st < 2; ++st) { const float pr = __shfl_xor(hre[st], 32), pi = __shfl_xor(him[st], 32); if (half != hf) { hre[st] = pr; him[st] = pi; } }
;         }
;     }
	v_pk_fma_f32 v[76:77], v[150:151], v[20:21], v[74:75] op_sel:[0,1,0] neg_lo:[0,0,1]
	v_add_f32_e32 v6, v72, v6
	v_add_f32_e32 v38, v73, v38
	v_add_f32_e32 v22, v76, v22
	v_add_f32_e32 v54, v77, v54
	v_pk_mul_f32 v[70:71], v[152:153], v[38:39] op_sel_hi:[1,0]
	v_pk_mul_f32 v[74:75], v[154:155], v[54:55] op_sel_hi:[1,0]
	v_pk_fma_f32 v[72:73], v[144:145], v[6:7], v[70:71] op_sel_hi:[1,0,1] neg_lo:[0,0,1]
	v_pk_fma_f32 v[76:77], v[150:151], v[22:23], v[74:75] op_sel_hi:[1,0,1] neg_lo:[0,0,1]
	v_add_f32_e32 v7, v72, v7
	v_add_f32_e32 v39, v73, v39
	v_add_f32_e32 v23, v76, v23
	v_add_f32_e32 v55, v77, v55
	v_pk_mul_f32 v[70:71], v[152:153], v[38:39] op_sel:[0,1]
	v_pk_mul_f32 v[74:75], v[154:155], v[54:55] op_sel:[0,1]
	v_pk_fma_f32 v[72:73], v[144:145], v[6:7], v[70:71] op_sel:[0,1,0] neg_lo:[0,0,1]
	v_pk_fma_f32 v[76:77], v[150:151], v[22:23], v[74:75] op_sel:[0,1,0] neg_lo:[0,0,1]
	v_add_f32_e32 v8, v72, v8
	v_add_f32_e32 v40, v73, v40
	v_add_f32_e32 v24, v76, v24
	v_add_f32_e32 v56, v77, v56
	v_pk_mul_f32 v[70:71], v[152:153], v[40:41] op_sel_hi:[1,0]
	v_pk_mul_f32 v[74:75], v[154:155], v[56:57] op_sel_hi:[1,0]
	v_pk_fma_f32 v[72:73], v[144:145], v[8:9], v[70:71] op_sel_hi:[1,0,1] neg_lo:[0,0,1]
	v_pk_fma_f32 v[76:77], v[150:151], v[24:25], v[74:75] op_sel_hi:[1,0,1] neg_lo:[0,0,1]
	v_add_f32_e32 v9, v72, v9
	v_add_f32_e32 v41, v73, v41
	v_add_f32_e32 v25, v76, v25
	v_add_f32_e32 v57, v77, v57
	v_pk_mul_f32 v[70:71], v[152:153], v[40:41] op_sel:[0,1]
	v_pk_mul_f32 v[74:75], v[154:155], v[56:57] op_sel:[0,1]
	v_pk_fma_f32 v[72:73], v[144:145], v[8:9], v[70:71] op_sel:[0,1,0] neg_lo:[0,0,1]
	v_pk_fma_f32 v[76:77], v[150:151], v[24:25], v[74:75] op_sel:[0,1,0] neg_lo:[0,0,1]
	v_add_f32_e32 v10, v72, v10
	v_add_f32_e32 v42, v73, v42
	v_add_f32_e32 v26, v76, v26
	v_add_f32_e32 v58, v77, v58
	v_pk_mul_f32 v[70:71], v[152:153], v[42:43] op_sel_hi:[1,0]
	v_pk_mul_f32 v[74:75], v[154:155], v[58:59] op_sel_hi:[1,0]
	v_pk_fma_f32 v[72:73], v[144:145], v[10:11], v[70:71] op_sel_hi:[1,0,1] neg_lo:[0,0,1]
	v_pk_fma_f32 v[76:77], v[150:151], v[26:27], v[74:75] op_sel_hi:[1,0,1] neg_lo:[0,0,1]
	v_add_f32_e32 v11, v72, v11
	v_add_f32_e32 v43, v73, v43
	v_add_f32_e32 v27, v76, v27
	v_add_f32_e32 v59, v77, v59
	v_pk_mul_f32 v[70:71], v[152:153], v[42:43] op_sel:[0,1]
	v_pk_mul_f32 v[74:75], v[154:155], v[58:59] op_sel:[0,1]
	v_pk_fma_f32 v[72:73], v[144:145], v[10:11], v[70:71] op_sel:[0,1,0] neg_lo:[0,0,1]
	v_pk_fma_f32 v[76:77], v[150:151], v[26:27], v[74:75] op_sel:[0,1,0] neg_lo:[0,0,1]
	v_add_f32_e32 v12, v72, v12
	v_add_f32_e32 v44, v73, v44
	v_add_f32_e32 v28, v76, v28
	v_add_f32_e32 v60, v77, v60
	v_pk_mul_f32 v[70:71], v[152:153], v[44:45] op_sel_hi:[1,0]
	v_pk_mul_f32 v[74:75], v[154:155], v[60:61] op_sel_hi:[1,0]
	v_pk_fma_f32 v[72:73], v[144:145], v[12:13], v[70:71] op_sel_hi:[1,0,1] neg_lo:[0,0,1]
	v_pk_fma_f32 v[76:77], v[150:151], v[28:29], v[74:75] op_sel_hi:[1,0,1] neg_lo:[0,0,1]
	v_add_f32_e32 v13, v72, v13
	v_add_f32_e32 v45, v73, v45
	v_add_f32_e32 v29, v76, v29
	v_add_f32_e32 v61, v77, v61
	v_pk_mul_f32 v[70:71], v[152:153], v[44:45] op_sel:[0,1]
	v_pk_mul_f32 v[74:75], v[154:155], v[60:61] op_sel:[0,1]
	v_pk_fma_f32 v[72:73], v[144:145], v[12:13], v[70:71] op_sel:[0,1,0] neg_lo:[0,0,1]
	v_pk_fma_f32 v[76:77], v[150:151], v[28:29], v[74:75] op_sel:[0,1,0] neg_lo:[0,0,1]
	v_add_f32_e32 v14, v72, v14
	v_add_f32_e32 v46, v73, v46
	v_add_f32_e32 v30, v76, v30
	v_add_f32_e32 v62, v77, v62
	v_pk_mul_f32 v[70:71], v[152:153], v[46:47] op_sel_hi:[1,0]
	v_pk_mul_f32 v[74:75], v[154:155], v[62:63] op_sel_hi:[1,0]
	v_pk_fma_f32 v[72:73], v[144:145], v[14:15], v[70:71] op_sel_hi:[1,0,1] neg_lo:[0,0,1]
	v_pk_fma_f32 v[76:77], v[150:151], v[30:31], v[74:75] op_sel_hi:[1,0,1] neg_lo:[0,0,1]
	v_add_f32_e32 v15, v72, v15
	v_add_f32_e32 v47, v73, v47
	v_add_f32_e32 v31, v76, v31
	v_add_f32_e32 v63, v77, v63
	s_mov_b64 exec, -1
	s_nop 1
	v_permlane32_swap_b32_e32 v66, v15
	v_permlane32_swap_b32_e32 v67, v47
	v_permlane32_swap_b32_e32 v68, v31
	v_permlane32_swap_b32_e32 v69, v63
	s_nop 0
	s_mov_b64 exec, s[8:9]
	v_pk_mul_f32 v[70:71], v[152:153], v[66:67] op_sel:[0,1]
	v_pk_mul_f32 v[74:75], v[154:155], v[68:69] op_sel:[0,1]
	v_pk_fma_f32 v[72:73], v[144:145], v[66:67], v[70:71] op_sel_hi:[1,0,1] neg_lo:[0,0,1]
	v_pk_fma_f32 v[76:77], v[150:151], v[68:69], v[74:75] op_sel_hi:[1,0,1] neg_lo:[0,0,1]
	v_add_f32_e32 v0, v72, v0
	v_add_f32_e32 v32, v73, v32
	v_add_f32_e32 v16, v76, v16
	v_add_f32_e32 v48, v77, v48
	v_pk_mul_f32 v[70:71], v[152:153], v[32:33] op_sel_hi:[1,0]
	v_pk_mul_f32 v[74:75], v[154:155], v[48:49] op_sel_hi:[1,0]
	v_pk_fma_f32 v[72:73], v[144:145], v[0:1], v[70:71] op_sel_hi:[1,0,1] neg_lo:[0,0,1]
	v_pk_fma_f32 v[76:77], v[150:151], v[16:17], v[74:75] op_sel_hi:[1,0,1] neg_lo:[0,0,1]
	v_add_f32_e32 v1, v72, v1
	v_add_f32_e32 v33, v73, v33
	v_add_f32_e32 v17, v76, v17
	v_add_f32_e32 v49, v77, v49
	v_pk_mul_f32 v[70:71], v[152:153], v[32:33] op_sel:[0,1]
	v_pk_mul_f32 v[74:75], v[154:155], v[48:49] op_sel:[0,1]
	v_pk_fma_f32 v[72:73], v[144:145], v[0:1], v[70:71] op_sel:[0,1,0] neg_lo:[0,0,1]
	v_pk_fma_f32 v[76:77], v[150:151], v[16:17], v[74:75] op_sel:[0,1,0] neg_lo:[0,0,1]
	v_add_f32_e32 v2, v72, v2
	v_add_f32_e32 v34, v73, v34
	v_add_f32_e32 v18, v76, v18
	v_add_f32_e32 v50, v77, v50
	v_pk_mul_f32 v[70:71], v[152:153], v[34:35] op_sel_hi:[1,0]
	v_pk_mul_f32 v[74:75], v[154:155], v[50:51] op_sel_hi:[1,0]
	v_pk_fma_f32 v[72:73], v[144:145], v[2:3], v[70:71] op_sel_hi:[1,0,1] neg_lo:[0,0,1]
; template <bool OUT>
; DI void s5_tile(const S5C& K, const float* U, int row0, int g, int nruns, int nvalid, float (&hre)[2], float (&him)[2], LAS bf16_t* Hs, const float* dvec, bf16_t* YC0, int lane) {
;     ...
;     for (int r = 0; r < 8; ++r) {
;         if (r < nruns) {
;             const int hf = r & 1, i0 = 4 * (r >> 1);
;             if (half == hf) {
; #pragma unroll
;                 for (int k = 0; k < 4; ++k)
; #pragma unroll
;                     for (int st = 0; st < 2; ++st) { const float nr = K.are[st] * hre[st] - K.aim[st] * him[st] + dre[st][i0 + k]; const float ni = K.are[st] * him[st] + K.aim[st] * hre[st] + dim[st][i0 + k];
;                         hre[st] = nr; him[st] = ni; dre[st][i0 + k] = nr; dim[st][i0 + k] = ni; }
;             }
; #pragma unroll
;             for (int st = 0; st < 2; ++st) { const float pr = __shfl_xor(hre[st], 32), pi = __shfl_xor(him[st], 32); if (half != hf) { hre[st] = pr; him[st] = pi; } }
;         }
;     }
	v_pk_fma_f32 v[76:77], v[150:151], v[18:19], v[74:75] op_sel_hi:[1,0,1] neg_lo:[0,0,1]
	v_add_f32_e32 v3, v72, v3
	v_add_f32_e32 v35, v73, v35
	v_add_f32_e32 v19, v76, v19
	v_add_f32_e32 v51, v77, v51
	v_pk_mul_f32 v[70:71], v[152:153], v[34:35] op_sel:[0,1]
	v_pk_mul_f32 v[74:75], v[154:155], v[50:51] op_sel:[0,1]
	v_pk_fma_f32 v[72:73], v[144:145], v[2:3], v[70:71] op_sel:[0,1,0] neg_lo:[0,0,1]
	v_pk_fma_f32 v[76:77], v[150:151], v[18:19], v[74:75] op_sel:[0,1,0] neg_lo:[0,0,1]
	v_add_f32_e32 v4, v72, v4
	v_add_f32_e32 v36, v73, v36
	v_add_f32_e32 v20, v76, v20
	v_add_f32_e32 v52, v77, v52
	v_pk_mul_f32 v[70:71], v[152:153], v[36:37] op_sel_hi:[1,0]
	v_pk_mul_f32 v[74:75], v[154:155], v[52:53] op_sel_hi:[1,0]
	v_pk_fma_f32 v[72:73], v[144:145], v[4:5], v[70:71] op_sel_hi:[1,0,1] neg_lo:[0,0,1]
	v_pk_fma_f32 v[76:77], v[150:151], v[20:21], v[74:75] op_sel_hi:[1,0,1] neg_lo:[0,0,1]
	v_add_f32_e32 v5, v72, v5
	v_add_f32_e32 v37, v73, v37
	v_add_f32_e32 v21, v76, v21
	v_add_f32_e32 v53, v77, v53
	v_pk_mul_f32 v[70:71], v[152:153], v[36:37] op_sel:[0,1]
	v_pk_mul_f32 v[74:75], v[154:155], v[52:53] op_sel:[0,1]
	v_pk_fma_f32 v[72:73], v[144:145], v[4:5], v[70:71] op_sel:[0,1,0] neg_lo:[0,0,1]
	v_pk_fma_f32 v[76:77], v[150:151], v[20:21], v[74:75] op_sel:[0,1,0] neg_lo:[0,0,1]
	v_add_f32_e32 v6, v72, v6
	v_add_f32_e32 v38, v73, v38
	v_add_f32_e32 v22, v76, v22
	v_add_f32_e32 v54, v77, v54
	v_pk_mul_f32 v[70:71], v[152:153], v[38:39] op_sel_hi:[1,0]
	v_pk_mul_f32 v[74:75], v[154:155], v[54:55] op_sel_hi:[1,0]
	v_pk_fma_f32 v[72:73], v[144:145], v[6:7], v[70:71] op_sel_hi:[1,0,1] neg_lo:[0,0,1]
	v_pk_fma_f32 v[76:77], v[150:151], v[22:23], v[74:75] op_sel_hi:[1,0,1] neg_lo:[0,0,1]
	v_add_f32_e32 v7, v72, v7
	v_add_f32_e32 v39, v73, v39
	v_add_f32_e32 v23, v76, v23
	v_add_f32_e32 v55, v77, v55
	v_pk_mul_f32 v[70:71], v[152:153], v[38:39] op_sel:[0,1]
	v_pk_mul_f32 v[74:75], v[154:155], v[54:55] op_sel:[0,1]
	v_pk_fma_f32 v[72:73], v[144:145], v[6:7], v[70:71] op_sel:[0,1,0] neg_lo:[0,0,1]
	v_pk_fma_f32 v[76:77], v[150:151], v[22:23], v[74:75] op_sel:[0,1,0] neg_lo:[0,0,1]
	v_add_f32_e32 v8, v72, v8
	v_add_f32_e32 v40, v73, v40
	v_add_f32_e32 v24, v76, v24
	v_add_f32_e32 v56, v77, v56
	v_pk_mul_f32 v[70:71], v[152:153], v[40:41] op_sel_hi:[1,0]
	v_pk_mul_f32 v[74:75], v[154:155], v[56:57] op_sel_hi:[1,0]
	v_pk_fma_f32 v[72:73], v[144:145], v[8:9], v[70:71] op_sel_hi:[1,0,1] neg_lo:[0,0,1]
	v_pk_fma_f32 v[76:77], v[150:151], v[24:25], v[74:75] op_sel_hi:[1,0,1] neg_lo:[0,0,1]
	v_add_f32_e32 v9, v72, v9
	v_add_f32_e32 v41, v73, v41
	v_add_f32_e32 v25, v76, v25
	v_add_f32_e32 v57, v77, v57
	v_pk_mul_f32 v[70:71], v[152:153], v[40:41] op_sel:[0,1]
	v_pk_mul_f32 v[74:75], v[154:155], v[56:57] op_sel:[0,1]
	v_pk_fma_f32 v[72:73], v[144:145], v[8:9], v[70:71] op_sel:[0,1,0] neg_lo:[0,0,1]
	v_pk_fma_f32 v[76:77], v[150:151], v[24:25], v[74:75] op_sel:[0,1,0] neg_lo:[0,0,1]
	v_add_f32_e32 v10, v72, v10
	v_add_f32_e32 v42, v73, v42
	v_add_f32_e32 v26, v76, v26
	v_add_f32_e32 v58, v77, v58
	v_pk_mul_f32 v[70:71], v[152:153], v[42:43] op_sel_hi:[1,0]
	v_pk_mul_f32 v[74:75], v[154:155], v[58:59] op_sel_hi:[1,0]
	v_pk_fma_f32 v[72:73], v[144:145], v[10:11], v[70:71] op_sel_hi:[1,0,1] neg_lo:[0,0,1]
	v_pk_fma_f32 v[76:77], v[150:151], v[26:27], v[74:75] op_sel_hi:[1,0,1] neg_lo:[0,0,1]
	v_add_f32_e32 v11, v72, v11
	v_add_f32_e32 v43, v73, v43
	v_add_f32_e32 v27, v76, v27
	v_add_f32_e32 v59, v77, v59
	v_pk_mul_f32 v[70:71], v[152:153], v[42:43] op_sel:[0,1]
	v_pk_mul_f32 v[74:75], v[154:155], v[58:59] op_sel:[0,1]
	v_pk_fma_f32 v[72:73], v[144:145], v[10:11], v[70:71] op_sel:[0,1,0] neg_lo:[0,0,1]
	v_pk_fma_f32 v[76:77], v[150:151], v[26:27], v[74:75] op_sel:[0,1,0] neg_lo:[0,0,1]
	v_add_f32_e32 v12, v72, v12
	v_add_f32_e32 v44, v73, v44
	v_add_f32_e32 v28, v76, v28
	v_add_f32_e32 v60, v77, v60
	v_pk_mul_f32 v[70:71], v[152:153], v[44:45] op_sel_hi:[1,0]
	v_pk_mul_f32 v[74:75], v[154:155], v[60:61] op_sel_hi:[1,0]
	v_pk_fma_f32 v[72:73], v[144:145], v[12:13], v[70:71] op_sel_hi:[1,0,1] neg_lo:[0,0,1]
	v_pk_fma_f32 v[76:77], v[150:151], v[28:29], v[74:75] op_sel_hi:[1,0,1] neg_lo:[0,0,1]
	v_add_f32_e32 v13, v72, v13
	v_add_f32_e32 v45, v73, v45
	v_add_f32_e32 v29, v76, v29
	v_add_f32_e32 v61, v77, v61
	v_pk_mul_f32 v[70:71], v[152:153], v[44:45] op_sel:[0,1]
	v_pk_mul_f32 v[74:75], v[154:155], v[60:61] op_sel:[0,1]
	v_pk_fma_f32 v[72:73], v[144:145], v[12:13], v[70:71] op_sel:[0,1,0] neg_lo:[0,0,1]
	v_pk_fma_f32 v[76:77], v[150:151], v[28:29], v[74:75] op_sel:[0,1,0] neg_lo:[0,0,1]
	v_add_f32_e32 v14, v72, v14
	v_add_f32_e32 v46, v73, v46
	v_add_f32_e32 v30, v76, v30
	v_add_f32_e32 v62, v77, v62
	v_pk_mul_f32 v[70:71], v[152:153], v[46:47] op_sel_hi:[1,0]
	v_pk_mul_f32 v[74:75], v[154:155], v[62:63] op_sel_hi:[1,0]
	v_pk_fma_f32 v[72:73], v[144:145], v[14:15], v[70:71] op_sel_hi:[1,0,1] neg_lo:[0,0,1]
	v_pk_fma_f32 v[76:77], v[150:151], v[30:31], v[74:75] op_sel_hi:[1,0,1] neg_lo:[0,0,1]
	v_add_f32_e32 v15, v72, v15
	v_add_f32_e32 v47, v73, v47
	v_add_f32_e32 v31, v76, v31
	v_add_f32_e32 v63, v77, v63
	s_mov_b64 exec, -1
	s_nop 1
	v_permlane32_swap_b32_e32 v15, v66
	v_permlane32_swap_b32_e32 v47, v67
	v_permlane32_swap_b32_e32 v31, v68
	v_permlane32_swap_b32_e32 v63, v69
	s_nop 0
	s_add_i32 s52, s52, 32
	s_cmpk_eq_i32 s52, 0x100
	s_cbranch_scc0 .Ls5a_tile
	v_mov_b32_e32 v78, v66
	v_mov_b32_e32 v79, v68
	v_mov_b32_e32 v80, v67
	v_mov_b32_e32 v81, v69

; #define LAS __attribute__((address_space(3)))
; DI bf16x8 pack8(const f32x4 a, const f32x4 b) { u32x4 p; p.x = cvt_pk_bf16(a[0], a[1]); p.y = cvt_pk_bf16(a[2], a[3]); p.z = cvt_pk_bf16(b[0], b[1]); p.w = cvt_pk_bf16(b[2], b[3]); return __builtin_bit_cast(bf16x8, p); }
; #define MFMA32(a, b, c) __builtin_amdgcn_mfma_f32_32x32x16_bf16((a), (b), (c), 0, 0, 0)
; template <bool OUT>
; DI void s5_tile(const S5C& K, const float* U, int row0, int g, int nruns, int nvalid, float (&hre)[2], float (&him)[2], LAS bf16_t* Hs, const float* dvec, bf16_t* YC0, int lane) {
;     const int tok = lane & 31, half = lane >> 5;
;     bf16x8 af = {0, 0, 0, 0, 0, 0, 0, 0};
;     if (tok < nvalid) { const float* up = U + (size_t)(row0 + tok) * 512 + g * 16 + half * 8; af = pack8(*(const f32x4*)up, *(const f32x4*)(up + 4)); }
;     f32x16 z16;
; #pragma unroll
;     for (int i = 0; i < 16; ++i) z16[i] = 0.f;
;     f32x16 dre[2], dim[2];
; #pragma unroll
;     for (int st = 0; st < 2; ++st) { dre[st] = MFMA32(af, K.bbf[st], z16); dim[st] = MFMA32(af, K.bbf[2 + st], z16); }
; #pragma unroll
;     for (int r = 0; r < 8; ++r) {
;         if (r < nruns) {
;             const int hf = r & 1, i0 = 4 * (r >> 1);
;             if (half == hf) {
; #pragma unroll
;                 for (int k = 0; k < 4; ++k)
; #pragma unroll
;                     for (int st = 0; st < 2; ++st) { const float nr = K.are[st] * hre[st] - K.aim[st] * him[st] + dre[st][i0 + k]; const float ni = K.are[st] * him[st] + K.aim[st] * hre[st] + dim[st][i0 + k];
;                         hre[st] = nr; him[st] = ni; dre[st][i0 + k] = nr; dim[st][i0 + k] = ni; }
;             }
; #pragma unroll
;             for (int st = 0; st < 2; ++st) { const float pr = __shfl_xor(hre[st], 32), pi = __shfl_xor(him[st], 32); if (half != hf) { hre[st] = pr; him[st] = pi; } }
;         }
;     }
.LBB0_932:
	s_or_b64 exec, exec, s[40:41]
	v_lshlrev_b32_e32 v0, 2, v172
	v_mov_b32_e32 v1, v97
	s_lshl_b32 s56, s45, 2
	v_lshl_add_u64 v[158:159], s[14:15], 0, v[0:1]
	v_or_b32_e32 v96, s45, v175
	v_lshl_add_u64 v[160:161], v[140:141], 0, s[56:57]
	v_add_u32_e32 v180, s44, v177
	s_mov_b32 s30, 0
	v_ashrrev_i32_e32 v1, 31, v179
	v_mov_b32_e32 v0, v179
	v_lshlrev_b64 v[0:1], 11, v[0:1]
	v_lshl_add_u64 v[4:5], v[158:159], 0, v[0:1]
	global_load_dwordx4 v[206:209], v[4:5], off
	global_load_dwordx4 v[210:213], v[4:5], off offset:16
	v_mov_b32_e32 v66, v164
	v_mov_b32_e32 v67, v162
	v_mov_b32_e32 v68, v165
	v_mov_b32_e32 v69, v163
	v_add_u32_e32 v94, v174, v176
	s_waitcnt vmcnt(0)
.Ls5b_tile:
	v_cvt_pk_bf16_f32 v86, v206, v207
	v_cvt_pk_bf16_f32 v87, v208, v209
	v_cvt_pk_bf16_f32 v88, v210, v211
	v_cvt_pk_bf16_f32 v89, v212, v213
	v_add_u32_e32 v92, s30, v179
	v_add_u32_e32 v92, 32, v92
	v_mfma_f32_32x32x16_bf16 v[0:15], v[86:89], v[98:101], 0
	v_mfma_f32_32x32x16_bf16 v[32:47], v[86:89], v[114:117], 0
	v_mfma_f32_32x32x16_bf16 v[16:31], v[86:89], v[106:109], 0
	v_mfma_f32_32x32x16_bf16 v[48:63], v[86:89], v[122:125], 0
	v_add_u32_e32 v226, s30, v180
	v_ashrrev_i32_e32 v227, 31, v226
	v_lshlrev_b64 v[228:229], 9, v[226:227]
	v_or_b32_e32 v228, v228, v96
	v_lshl_add_u64 v[230:231], v[228:229], 1, s[16:17]
	v_lshl_add_u64 v[228:229], v[228:229], 2, s[4:5]
	global_load_dwordx4 v[214:217], v[228:229], off
	v_add_u32_e32 v226, 16, v226
	v_ashrrev_i32_e32 v227, 31, v226
	v_lshlrev_b64 v[228:229], 9, v[226:227]
	v_or_b32_e32 v228, v228, v96
	v_lshl_add_u64 v[232:233], v[228:229], 1, s[16:17]
	v_lshl_add_u64 v[228:229], v[228:229], 2, s[4:5]
	global_load_dwordx4 v[218:221], v[228:229], off
	global_load_dwordx4 v[222:225], v[160:161], off
	v_ashrrev_i32_e32 v93, 31, v92
	v_lshlrev_b64 v[92:93], 11, v[92:93]
	v_lshl_add_u64 v[92:93], v[158:159], 0, v[92:93]
	global_load_dwordx4 v[206:209], v[92:93], off
	global_load_dwordx4 v[210:213], v[92:93], off offset:16
	s_mov_b64 exec, s[6:7]
	v_pk_mul_f32 v[70:71], v[152:153], v[66:67] op_sel:[0,1]
	v_pk_mul_f32 v[74:75], v[154:155], v[68:69] op_sel:[0,1]
	v_pk_fma_f32 v[72:73], v[144:145], v[66:67], v[70:71] op_sel_hi:[1,0,1] neg_lo:[0,0,1]
	v_pk_fma_f32 v[76:77], v[150:151], v[68:69], v[74:75] op_sel_hi:[1,0,1] neg_lo:[0,0,1]
	v_add_f32_e32 v0, v72, v0
	v_add_f32_e32 v32, v73, v32
	v_add_f32_e32 v16, v76, v16
	v_add_f32_e32 v48, v77, v48
	v_pk_mul_f32 v[70:71], v[152:153], v[32:33] op_sel_hi:[1,0]
	v_pk_mul_f32 v[74:75], v[154:155], v[48:49] op_sel_hi:[1,0]
	v_pk_fma_f32 v[72:73], v[144:145], v[0:1], v[70:71] op_sel_hi:[1,0,1] neg_lo:[0,0,1]
	v_pk_fma_f32 v[76:77], v[150:151], v[16:17], v[74:75] op_sel_hi:[1,0,1] neg_lo:[0,0,1]
	v_add_f32_e32 v1, v72, v1
	v_add_f32_e32 v33, v73, v33
	v_add_f32_e32 v17, v76, v17
	v_add_f32_e32 v49, v77, v49
	v_pk_mul_f32 v[70:71], v[152:153], v[32:33] op_sel:[0,1]
	v_pk_mul_f32 v[74:75], v[154:155], v[48:49] op_sel:[0,1]
	v_pk_fma_f32 v[72:73], v[144:145], v[0:1], v[70:71] op_sel:[0,1,0] neg_lo:[0,0,1]
	v_pk_fma_f32 v[76:77], v[150:151], v[16:17], v[74:75] op_sel:[0,1,0] neg_lo:[0,0,1]
	v_add_f32_e32 v2, v72, v2
	v_add_f32_e32 v34, v73, v34
	v_add_f32_e32 v18, v76, v18
	v_add_f32_e32 v50, v77, v50
	v_pk_mul_f32 v[70:71], v[152:153], v[34:35] op_sel_hi:[1,0]
	v_pk_mul_f32 v[74:75], v[154:155], v[50:51] op_sel_hi:[1,0]
	v_pk_fma_f32 v[72:73], v[144:145], v[2:3], v[70:71] op_sel_hi:[1,0,1] neg_lo:[0,0,1]
	v_pk_fma_f32 v[76:77], v[150:151], v[18:19], v[74:75] op_sel_hi:[1,0,1] neg_lo:[0,0,1]
	v_add_f32_e32 v3, v72, v3
	v_add_f32_e32 v35, v73, v35
	v_add_f32_e32 v19, v76, v19
	v_add_f32_e32 v51, v77, v51
	v_pk_mul_f32 v[70:71], v[152:153], v[34:35] op_sel:[0,1]
	v_pk_mul_f32 v[74:75], v[154:155], v[50:51] op_sel:[0,1]
	v_pk_fma_f32 v[72:73], v[144:145], v[2:3], v[70:71] op_sel:[0,1,0] neg_lo:[0,0,1]
	v_pk_fma_f32 v[76:77], v[150:151], v[18:19], v[74:75] op_sel:[0,1,0] neg_lo:[0,0,1]
	v_add_f32_e32 v4, v72, v4
	v_add_f32_e32 v36, v73, v36
	v_add_f32_e32 v20, v76, v20
	v_add_f32_e32 v52, v77, v52
	v_pk_mul_f32 v[70:71], v[152:153], v[36:37] op_sel_hi:[1,0]
	v_pk_mul_f32 v[74:75], v[154:155], v[52:53] op_sel_hi:[1,0]
	v_pk_fma_f32 v[72:73], v[144:145], v[4:5], v[70:71] op_sel_hi:[1,0,1] neg_lo:[0,0,1]
	v_pk_fma_f32 v[76:77], v[150:151], v[20:21], v[74:75] op_sel_hi:[1,0,1] neg_lo:[0,0,1]
	v_add_f32_e32 v5, v72, v5
	v_add_f32_e32 v37, v73, v37
	v_add_f32_e32 v21, v76, v21
	v_add_f32_e32 v53, v77, v53
	v_pk_mul_f32 v[70:71], v[152:153], v[36:37] op_sel:[0,1]
	v_pk_mul_f32 v[74:75], v[154:155], v[52:53] op_sel:[0,1]
	v_pk_fma_f32 v[72:73], v[144:145], v[4:5], v[70:71] op_sel:[0,1,0] neg_lo:[0,0,1]
	v_pk_fma_f32 v[76:77], v[150:151], v[20:21], v[74:75] op_sel:[0,1,0] neg_lo:[0,0,1]
	v_add_f32_e32 v6, v72, v6
	v_add_f32_e32 v38, v73, v38
	v_add_f32_e32 v22, v76, v22
	v_add_f32_e32 v54, v77, v54
	v_pk_mul_f32 v[70:71], v[152:153], v[38:39] op_sel_hi:[1,0]
	v_pk_mul_f32 v[74:75], v[154:155], v[54:55] op_sel_hi:[1,0]
	v_pk_fma_f32 v[72:73], v[144:145], v[6:7], v[70:71] op_sel_hi:[1,0,1] neg_lo:[0,0,1]
	v_pk_fma_f32 v[76:77], v[150:151], v[22:23], v[74:75] op_sel_hi:[1,0,1] neg_lo:[0,0,1]
	v_add_f32_e32 v7, v72, v7
	v_add_f32_e32 v39, v73, v39
	v_add_f32_e32 v23, v76, v23
	v_add_f32_e32 v55, v77, v55
	v_pk_mul_f32 v[70:71], v[152:153], v[38:39] op_sel:[0,1]
	v_pk_mul_f32 v[74:75], v[154:155], v[54:55] op_sel:[0,1]
	v_pk_fma_f32 v[72:73], v[144:145], v[6:7], v[70:71] op_sel:[0,1,0] neg_lo:[0,0,1]
	v_pk_fma_f32 v[76:77], v[150:151], v[22:23], v[74:75] op_sel:[0,1,0] neg_lo:[0,0,1]
	v_add_f32_e32 v8, v72, v8
	v_add_f32_e32 v40, v73, v40
	v_add_f32_e32 v24, v76, v24
	v_add_f32_e32 v56, v77, v56
; template <bool OUT>
; DI void s5_tile(const S5C& K, const float* U, int row0, int g, int nruns, int nvalid, float (&hre)[2], float (&him)[2], LAS bf16_t* Hs, const float* dvec, bf16_t* YC0, int lane) {
;     ...
;     for (int r = 0; r < 8; ++r) {
;         if (r < nruns) {
;             const int hf = r & 1, i0 = 4 * (r >> 1);
;             if (half == hf) {
; #pragma unroll
;                 for (int k = 0; k < 4; ++k)
; #pragma unroll
;                     for (int st = 0; st < 2; ++st) { const float nr = K.are[st] * hre[st] - K.aim[st] * him[st] + dre[st][i0 + k]; const float ni = K.are[st] * him[st] + K.aim[st] * hre[st] + dim[st][i0 + k];
;                         hre[st] = nr; him[st] = ni; dre[st][i0 + k] = nr; dim[st][i0 + k] = ni; }
;             }
; #pragma unroll
;             for (int st = 0; st < 2; ++st) { const float pr = __shfl_xor(hre[st], 32), pi = __shfl_xor(him[st], 32); if (half != hf) { hre[st] = pr; him[st] = pi; } }
;         }
;     }
	v_pk_mul_f32 v[70:71], v[152:153], v[40:41] op_sel_hi:[1,0]
	v_pk_mul_f32 v[74:75], v[154:155], v[56:57] op_sel_hi:[1,0]
	v_pk_fma_f32 v[72:73], v[144:145], v[8:9], v[70:71] op_sel_hi:[1,0,1] neg_lo:[0,0,1]
	v_pk_fma_f32 v[76:77], v[150:151], v[24:25], v[74:75] op_sel_hi:[1,0,1] neg_lo:[0,0,1]
	v_add_f32_e32 v9, v72, v9
	v_add_f32_e32 v41, v73, v41
	v_add_f32_e32 v25, v76, v25
	v_add_f32_e32 v57, v77, v57
	v_pk_mul_f32 v[70:71], v[152:153], v[40:41] op_sel:[0,1]
	v_pk_mul_f32 v[74:75], v[154:155], v[56:57] op_sel:[0,1]
	v_pk_fma_f32 v[72:73], v[144:145], v[8:9], v[70:71] op_sel:[0,1,0] neg_lo:[0,0,1]
	v_pk_fma_f32 v[76:77], v[150:151], v[24:25], v[74:75] op_sel:[0,1,0] neg_lo:[0,0,1]
	v_add_f32_e32 v10, v72, v10
	v_add_f32_e32 v42, v73, v42
	v_add_f32_e32 v26, v76, v26
	v_add_f32_e32 v58, v77, v58
	v_pk_mul_f32 v[70:71], v[152:153], v[42:43] op_sel_hi:[1,0]
	v_pk_mul_f32 v[74:75], v[154:155], v[58:59] op_sel_hi:[1,0]
	v_pk_fma_f32 v[72:73], v[144:145], v[10:11], v[70:71] op_sel_hi:[1,0,1] neg_lo:[0,0,1]
	v_pk_fma_f32 v[76:77], v[150:151], v[26:27], v[74:75] op_sel_hi:[1,0,1] neg_lo:[0,0,1]
	v_add_f32_e32 v11, v72, v11
	v_add_f32_e32 v43, v73, v43
	v_add_f32_e32 v27, v76, v27
	v_add_f32_e32 v59, v77, v59
	v_pk_mul_f32 v[70:71], v[152:153], v[42:43] op_sel:[0,1]
	v_pk_mul_f32 v[74:75], v[154:155], v[58:59] op_sel:[0,1]
	v_pk_fma_f32 v[72:73], v[144:145], v[10:11], v[70:71] op_sel:[0,1,0] neg_lo:[0,0,1]
	v_pk_fma_f32 v[76:77], v[150:151], v[26:27], v[74:75] op_sel:[0,1,0] neg_lo:[0,0,1]
	v_add_f32_e32 v12, v72, v12
	v_add_f32_e32 v44, v73, v44
	v_add_f32_e32 v28, v76, v28
	v_add_f32_e32 v60, v77, v60
	v_pk_mul_f32 v[70:71], v[152:153], v[44:45] op_sel_hi:[1,0]
	v_pk_mul_f32 v[74:75], v[154:155], v[60:61] op_sel_hi:[1,0]
	v_pk_fma_f32 v[72:73], v[144:145], v[12:13], v[70:71] op_sel_hi:[1,0,1] neg_lo:[0,0,1]
	v_pk_fma_f32 v[76:77], v[150:151], v[28:29], v[74:75] op_sel_hi:[1,0,1] neg_lo:[0,0,1]
	v_add_f32_e32 v13, v72, v13
	v_add_f32_e32 v45, v73, v45
	v_add_f32_e32 v29, v76, v29
	v_add_f32_e32 v61, v77, v61
	v_pk_mul_f32 v[70:71], v[152:153], v[44:45] op_sel:[0,1]
	v_pk_mul_f32 v[74:75], v[154:155], v[60:61] op_sel:[0,1]
	v_pk_fma_f32 v[72:73], v[144:145], v[12:13], v[70:71] op_sel:[0,1,0] neg_lo:[0,0,1]
	v_pk_fma_f32 v[76:77], v[150:151], v[28:29], v[74:75] op_sel:[0,1,0] neg_lo:[0,0,1]
	v_add_f32_e32 v14, v72, v14
	v_add_f32_e32 v46, v73, v46
	v_add_f32_e32 v30, v76, v30
	v_add_f32_e32 v62, v77, v62
	v_pk_mul_f32 v[70:71], v[152:153], v[46:47] op_sel_hi:[1,0]
	v_pk_mul_f32 v[74:75], v[154:155], v[62:63] op_sel_hi:[1,0]
	v_pk_fma_f32 v[72:73], v[144:145], v[14:15], v[70:71] op_sel_hi:[1,0,1] neg_lo:[0,0,1]
	v_pk_fma_f32 v[76:77], v[150:151], v[30:31], v[74:75] op_sel_hi:[1,0,1] neg_lo:[0,0,1]
	v_add_f32_e32 v15, v72, v15
	v_add_f32_e32 v47, v73, v47
	v_add_f32_e32 v31, v76, v31
	v_add_f32_e32 v63, v77, v63
	s_mov_b64 exec, -1
	v_mov_b32_e32 v82, v15
	v_mov_b32_e32 v83, v47
	v_mov_b32_e32 v84, v31
	v_mov_b32_e32 v85, v63
	s_nop 1
	v_permlane32_swap_b32_e32 v66, v82
	v_permlane32_swap_b32_e32 v67, v83
	v_permlane32_swap_b32_e32 v68, v84
	v_permlane32_swap_b32_e32 v69, v85
	s_nop 0
	s_mov_b64 exec, s[8:9]
	v_pk_mul_f32 v[70:71], v[152:153], v[66:67] op_sel:[0,1]
	v_pk_mul_f32 v[74:75], v[154:155], v[68:69] op_sel:[0,1]
	v_pk_fma_f32 v[72:73], v[144:145], v[66:67], v[70:71] op_sel_hi:[1,0,1] neg_lo:[0,0,1]
	v_pk_fma_f32 v[76:77], v[150:151], v[68:69], v[74:75] op_sel_hi:[1,0,1] neg_lo:[0,0,1]
	v_add_f32_e32 v0, v72, v0
	v_add_f32_e32 v32, v73, v32
	v_add_f32_e32 v16, v76, v16
	v_add_f32_e32 v48, v77, v48
	v_pk_mul_f32 v[70:71], v[152:153], v[32:33] op_sel_hi:[1,0]
	v_pk_mul_f32 v[74:75], v[154:155], v[48:49] op_sel_hi:[1,0]
	v_pk_fma_f32 v[72:73], v[144:145], v[0:1], v[70:71] op_sel_hi:[1,0,1] neg_lo:[0,0,1]
	v_pk_fma_f32 v[76:77], v[150:151], v[16:17], v[74:75] op_sel_hi:[1,0,1] neg_lo:[0,0,1]
	v_add_f32_e32 v1, v72, v1
	v_add_f32_e32 v33, v73, v33
	v_add_f32_e32 v17, v76, v17
	v_add_f32_e32 v49, v77, v49
	v_pk_mul_f32 v[70:71], v[152:153], v[32:33] op_sel:[0,1]
	v_pk_mul_f32 v[74:75], v[154:155], v[48:49] op_sel:[0,1]
	v_pk_fma_f32 v[72:73], v[144:145], v[0:1], v[70:71] op_sel:[0,1,0] neg_lo:[0,0,1]
	v_pk_fma_f32 v[76:77], v[150:151], v[16:17], v[74:75] op_sel:[0,1,0] neg_lo:[0,0,1]
	v_add_f32_e32 v2, v72, v2
	v_add_f32_e32 v34, v73, v34
	v_add_f32_e32 v18, v76, v18
	v_add_f32_e32 v50, v77, v50
	v_pk_mul_f32 v[70:71], v[152:153], v[34:35] op_sel_hi:[1,0]
	v_pk_mul_f32 v[74:75], v[154:155], v[50:51] op_sel_hi:[1,0]
	v_pk_fma_f32 v[72:73], v[144:145], v[2:3], v[70:71] op_sel_hi:[1,0,1] neg_lo:[0,0,1]
	v_pk_fma_f32 v[76:77], v[150:151], v[18:19], v[74:75] op_sel_hi:[1,0,1] neg_lo:[0,0,1]
	v_add_f32_e32 v3, v72, v3
	v_add_f32_e32 v35, v73, v35
	v_add_f32_e32 v19, v76, v19
	v_add_f32_e32 v51, v77, v51
	v_pk_mul_f32 v[70:71], v[152:153], v[34:35] op_sel:[0,1]
	v_pk_mul_f32 v[74:75], v[154:155], v[50:51] op_sel:[0,1]
	v_pk_fma_f32 v[72:73], v[144:145], v[2:3], v[70:71] op_sel:[0,1,0] neg_lo:[0,0,1]
	v_pk_fma_f32 v[76:77], v[150:151], v[18:19], v[74:75] op_sel:[0,1,0] neg_lo:[0,0,1]
	v_add_f32_e32 v4, v72, v4
	v_add_f32_e32 v36, v73, v36
	v_add_f32_e32 v20, v76, v20
	v_add_f32_e32 v52, v77, v52
	v_pk_mul_f32 v[70:71], v[152:153], v[36:37] op_sel_hi:[1,0]
	v_pk_mul_f32 v[74:75], v[154:155], v[52:53] op_sel_hi:[1,0]
	v_pk_fma_f32 v[72:73], v[144:145], v[4:5], v[70:71] op_sel_hi:[1,0,1] neg_lo:[0,0,1]
	v_pk_fma_f32 v[76:77], v[150:151], v[20:21], v[74:75] op_sel_hi:[1,0,1] neg_lo:[0,0,1]
	v_add_f32_e32 v5, v72, v5
	v_add_f32_e32 v37, v73, v37
	v_add_f32_e32 v21, v76, v21
	v_add_f32_e32 v53, v77, v53
	v_pk_mul_f32 v[70:71], v[152:153], v[36:37] op_sel:[0,1]
; #define LAS __attribute__((address_space(3)))
; DI unsigned f2bf(float f) { unsigned u = __float_as_uint(f); return (u + 0x7fffu + ((u >> 16) & 1u)) >> 16; }
; template <bool OUT>
; DI void s5_tile(const S5C& K, const float* U, int row0, int g, int nruns, int nvalid, float (&hre)[2], float (&him)[2], LAS bf16_t* Hs, const float* dvec, bf16_t* YC0, int lane) {
;     ...
;     for (int r = 0; r < 8; ++r) {
;         if (r < nruns) {
;             const int hf = r & 1, i0 = 4 * (r >> 1);
;             if (half == hf) {
; #pragma unroll
;                 for (int k = 0; k < 4; ++k)
; #pragma unroll
;                     for (int st = 0; st < 2; ++st) { const float nr = K.are[st] * hre[st] - K.aim[st] * him[st] + dre[st][i0 + k]; const float ni = K.are[st] * him[st] + K.aim[st] * hre[st] + dim[st][i0 + k];
;                         hre[st] = nr; him[st] = ni; dre[st][i0 + k] = nr; dim[st][i0 + k] = ni; }
;             }
; #pragma unroll
;             for (int st = 0; st < 2; ++st) { const float pr = __shfl_xor(hre[st], 32), pi = __shfl_xor(him[st], 32); if (half != hf) { hre[st] = pr; him[st] = pi; } }
;         }
;     }
;     if (OUT) {
; #pragma unroll
;         for (int i = 0; i < 16; ++i) { const int tr = (i & 3) + 8 * (i >> 2) + 4 * half; LAS bf16_t* hp = Hs + tr * 136 + tok;
; #pragma unroll
;             for (int st = 0; st < 2; ++st) { hp[st * 32] = (bf16_t)f2bf(dre[st][i]); hp[64 + st * 32] = (bf16_t)f2bf(dim[st][i]); } }
	v_pk_mul_f32 v[74:75], v[154:155], v[52:53] op_sel:[0,1]
	v_pk_fma_f32 v[72:73], v[144:145], v[4:5], v[70:71] op_sel:[0,1,0] neg_lo:[0,0,1]
	v_pk_fma_f32 v[76:77], v[150:151], v[20:21], v[74:75] op_sel:[0,1,0] neg_lo:[0,0,1]
	v_add_f32_e32 v6, v72, v6
	v_add_f32_e32 v38, v73, v38
	v_add_f32_e32 v22, v76, v22
	v_add_f32_e32 v54, v77, v54
	v_pk_mul_f32 v[70:71], v[152:153], v[38:39] op_sel_hi:[1,0]
	v_pk_mul_f32 v[74:75], v[154:155], v[54:55] op_sel_hi:[1,0]
	v_pk_fma_f32 v[72:73], v[144:145], v[6:7], v[70:71] op_sel_hi:[1,0,1] neg_lo:[0,0,1]
	v_pk_fma_f32 v[76:77], v[150:151], v[22:23], v[74:75] op_sel_hi:[1,0,1] neg_lo:[0,0,1]
	v_add_f32_e32 v7, v72, v7
	v_add_f32_e32 v39, v73, v39
	v_add_f32_e32 v23, v76, v23
	v_add_f32_e32 v55, v77, v55
	v_pk_mul_f32 v[70:71], v[152:153], v[38:39] op_sel:[0,1]
	v_pk_mul_f32 v[74:75], v[154:155], v[54:55] op_sel:[0,1]
	v_pk_fma_f32 v[72:73], v[144:145], v[6:7], v[70:71] op_sel:[0,1,0] neg_lo:[0,0,1]
	v_pk_fma_f32 v[76:77], v[150:151], v[22:23], v[74:75] op_sel:[0,1,0] neg_lo:[0,0,1]
	v_add_f32_e32 v8, v72, v8
	v_add_f32_e32 v40, v73, v40
	v_add_f32_e32 v24, v76, v24
	v_add_f32_e32 v56, v77, v56
	v_pk_mul_f32 v[70:71], v[152:153], v[40:41] op_sel_hi:[1,0]
	v_pk_mul_f32 v[74:75], v[154:155], v[56:57] op_sel_hi:[1,0]
	v_pk_fma_f32 v[72:73], v[144:145], v[8:9], v[70:71] op_sel_hi:[1,0,1] neg_lo:[0,0,1]
	v_pk_fma_f32 v[76:77], v[150:151], v[24:25], v[74:75] op_sel_hi:[1,0,1] neg_lo:[0,0,1]
	v_add_f32_e32 v9, v72, v9
	v_add_f32_e32 v41, v73, v41
	v_add_f32_e32 v25, v76, v25
	v_add_f32_e32 v57, v77, v57
	v_pk_mul_f32 v[70:71], v[152:153], v[40:41] op_sel:[0,1]
	v_pk_mul_f32 v[74:75], v[154:155], v[56:57] op_sel:[0,1]
	v_pk_fma_f32 v[72:73], v[144:145], v[8:9], v[70:71] op_sel:[0,1,0] neg_lo:[0,0,1]
	v_pk_fma_f32 v[76:77], v[150:151], v[24:25], v[74:75] op_sel:[0,1,0] neg_lo:[0,0,1]
	v_add_f32_e32 v10, v72, v10
	v_add_f32_e32 v42, v73, v42
	v_add_f32_e32 v26, v76, v26
	v_add_f32_e32 v58, v77, v58
	v_pk_mul_f32 v[70:71], v[152:153], v[42:43] op_sel_hi:[1,0]
	v_pk_mul_f32 v[74:75], v[154:155], v[58:59] op_sel_hi:[1,0]
	v_pk_fma_f32 v[72:73], v[144:145], v[10:11], v[70:71] op_sel_hi:[1,0,1] neg_lo:[0,0,1]
	v_pk_fma_f32 v[76:77], v[150:151], v[26:27], v[74:75] op_sel_hi:[1,0,1] neg_lo:[0,0,1]
	v_add_f32_e32 v11, v72, v11
	v_add_f32_e32 v43, v73, v43
	v_add_f32_e32 v27, v76, v27
	v_add_f32_e32 v59, v77, v59
	v_pk_mul_f32 v[70:71], v[152:153], v[42:43] op_sel:[0,1]
	v_pk_mul_f32 v[74:75], v[154:155], v[58:59] op_sel:[0,1]
	v_pk_fma_f32 v[72:73], v[144:145], v[10:11], v[70:71] op_sel:[0,1,0] neg_lo:[0,0,1]
	v_pk_fma_f32 v[76:77], v[150:151], v[26:27], v[74:75] op_sel:[0,1,0] neg_lo:[0,0,1]
	v_add_f32_e32 v12, v72, v12
	v_add_f32_e32 v44, v73, v44
	v_add_f32_e32 v28, v76, v28
	v_add_f32_e32 v60, v77, v60
	v_pk_mul_f32 v[70:71], v[152:153], v[44:45] op_sel_hi:[1,0]
	v_pk_mul_f32 v[74:75], v[154:155], v[60:61] op_sel_hi:[1,0]
	v_pk_fma_f32 v[72:73], v[144:145], v[12:13], v[70:71] op_sel_hi:[1,0,1] neg_lo:[0,0,1]
	v_pk_fma_f32 v[76:77], v[150:151], v[28:29], v[74:75] op_sel_hi:[1,0,1] neg_lo:[0,0,1]
	v_add_f32_e32 v13, v72, v13
	v_add_f32_e32 v45, v73, v45
	v_add_f32_e32 v29, v76, v29
	v_add_f32_e32 v61, v77, v61
	v_pk_mul_f32 v[70:71], v[152:153], v[44:45] op_sel:[0,1]
	v_pk_mul_f32 v[74:75], v[154:155], v[60:61] op_sel:[0,1]
	v_pk_fma_f32 v[72:73], v[144:145], v[12:13], v[70:71] op_sel:[0,1,0] neg_lo:[0,0,1]
	v_pk_fma_f32 v[76:77], v[150:151], v[28:29], v[74:75] op_sel:[0,1,0] neg_lo:[0,0,1]
	v_add_f32_e32 v14, v72, v14
	v_add_f32_e32 v46, v73, v46
	v_add_f32_e32 v30, v76, v30
	v_add_f32_e32 v62, v77, v62
	v_pk_mul_f32 v[70:71], v[152:153], v[46:47] op_sel_hi:[1,0]
	v_pk_mul_f32 v[74:75], v[154:155], v[62:63] op_sel_hi:[1,0]
	v_pk_fma_f32 v[72:73], v[144:145], v[14:15], v[70:71] op_sel_hi:[1,0,1] neg_lo:[0,0,1]
	v_pk_fma_f32 v[76:77], v[150:151], v[30:31], v[74:75] op_sel_hi:[1,0,1] neg_lo:[0,0,1]
	v_add_f32_e32 v15, v72, v15
	v_add_f32_e32 v47, v73, v47
	v_add_f32_e32 v31, v76, v31
	v_add_f32_e32 v63, v77, v63
	s_mov_b64 exec, -1
	v_mov_b32_e32 v82, v15
	v_mov_b32_e32 v83, v47
	v_mov_b32_e32 v84, v31
	v_mov_b32_e32 v85, v63
	s_nop 1
	v_permlane32_swap_b32_e32 v82, v66
	v_permlane32_swap_b32_e32 v83, v67
	v_permlane32_swap_b32_e32 v84, v68
	v_permlane32_swap_b32_e32 v85, v69
	s_nop 0
	v_cvt_pk_bf16_f32 v82, v0, v32
	v_cvt_pk_bf16_f32 v83, v16, v48
	ds_write_b16 v90, v82
	ds_write_b16_d16_hi v90, v82 offset:128
	ds_write_b16 v90, v83 offset:64
	ds_write_b16_d16_hi v90, v83 offset:192
	v_cvt_pk_bf16_f32 v84, v1, v33
	v_cvt_pk_bf16_f32 v85, v17, v49
	ds_write_b16 v90, v84 offset:272
	ds_write_b16_d16_hi v90, v84 offset:400
	ds_write_b16 v90, v85 offset:336
	ds_write_b16_d16_hi v90, v85 offset:464
	v_cvt_pk_bf16_f32 v82, v2, v34
	v_cvt_pk_bf16_f32 v83, v18, v50
	ds_write_b16 v90, v82 offset:544
	ds_write_b16_d16_hi v90, v82 offset:672
	ds_write_b16 v90, v83 offset:608
	ds_write_b16_d16_hi v90, v83 offset:736
	v_cvt_pk_bf16_f32 v84, v3, v35
	v_cvt_pk_bf16_f32 v85, v19, v51
	ds_write_b16 v90, v84 offset:816
	ds_write_b16_d16_hi v90, v84 offset:944
	ds_write_b16 v90, v85 offset:880
	ds_write_b16_d16_hi v90, v85 offset:1008
	v_cvt_pk_bf16_f32 v82, v4, v36
	v_cvt_pk_bf16_f32 v83, v20, v52
	ds_write_b16 v90, v82 offset:1088
	ds_write_b16_d16_hi v90, v82 offset:1216
	ds_write_b16 v90, v83 offset:1152
	ds_write_b16_d16_hi v90, v83 offset:1280
	v_cvt_pk_bf16_f32 v84, v5, v37
	v_cvt_pk_bf16_f32 v85, v21, v53
	ds_write_b16 v90, v84 offset:1360
	ds_write_b16_d16_hi v90, v84 offset:1488
	ds_write_b16 v90, v85 offset:1424
	ds_write_b16_d16_hi v90, v85 offset:1552
	v_cvt_pk_bf16_f32 v82, v6, v38
	v_cvt_pk_bf16_f32 v83, v22, v54
; __device__ __forceinline__ void st_bf4(bf16_t* p, const f32x4 v) { u32x2 w; w.x = cvt_pk_bf16(v[0], v[1]); w.y = cvt_pk_bf16(v[2], v[3]); *(u32x2*)p = w; }
; #define LAS __attribute__((address_space(3)))
; DI unsigned f2bf(float f) { unsigned u = __float_as_uint(f); return (u + 0x7fffu + ((u >> 16) & 1u)) >> 16; }
; #define MFMA16(a, b, c) __builtin_amdgcn_mfma_f32_16x16x32_bf16((a), (b), (c), 0, 0, 0)
; DI float gelu_tanh(float y) { const float z = 1.5957691216057308f * (y + 0.044715f * y * y * y); return y * sigm(z); }
; template <bool OUT>
; DI void s5_tile(const S5C& K, const float* U, int row0, int g, int nruns, int nvalid, float (&hre)[2], float (&him)[2], LAS bf16_t* Hs, const float* dvec, bf16_t* YC0, int lane) {
;     ...
;     if (OUT) {
; #pragma unroll
;         for (int i = 0; i < 16; ++i) { const int tr = (i & 3) + 8 * (i >> 2) + 4 * half; LAS bf16_t* hp = Hs + tr * 136 + tok;
; #pragma unroll
;             for (int st = 0; st < 2; ++st) { hp[st * 32] = (bf16_t)f2bf(dre[st][i]); hp[64 + st * 32] = (bf16_t)f2bf(dim[st][i]); } }
;         const int l15 = lane & 15, quad = lane >> 4;
; #pragma unroll
;         for (int tt = 0; tt < 2; ++tt) {
;             if (tt * 16 < nvalid) {
;                 f32x4 acc = {0.f, 0.f, 0.f, 0.f};
; #pragma unroll
;                 for (int ks = 0; ks < 4; ++ks) { const bf16x8 hf8 = *(const LAS bf16x8*)(Hs + (tt * 16 + l15) * 136 + ks * 32 + quad * 8); acc = MFMA16(K.cf[ks], hf8, acc); }
;                 const int tk = tt * 16 + l15;
;                 if (tk < nvalid) { const size_t ro = (size_t)(row0 + tk) * 512 + g * 16 + quad * 4;
;                     const f32x4 u4 = *(const f32x4*)(U + ro), d4 = *(const f32x4*)(dvec + quad * 4); f32x4 y = acc + d4 * u4;
;                     y[0] = gelu_tanh(y[0]); y[1] = gelu_tanh(y[1]); y[2] = gelu_tanh(y[2]); y[3] = gelu_tanh(y[3]);
;                     st_bf4(YC0 + ro, y); }
	ds_write_b16 v90, v82 offset:1632
	ds_write_b16_d16_hi v90, v82 offset:1760
	ds_write_b16 v90, v83 offset:1696
	ds_write_b16_d16_hi v90, v83 offset:1824
	v_cvt_pk_bf16_f32 v84, v7, v39
	v_cvt_pk_bf16_f32 v85, v23, v55
	ds_write_b16 v90, v84 offset:1904
	ds_write_b16_d16_hi v90, v84 offset:2032
	ds_write_b16 v90, v85 offset:1968
	ds_write_b16_d16_hi v90, v85 offset:2096
	v_cvt_pk_bf16_f32 v82, v8, v40
	v_cvt_pk_bf16_f32 v83, v24, v56
	ds_write_b16 v90, v82 offset:2176
	ds_write_b16_d16_hi v90, v82 offset:2304
	ds_write_b16 v90, v83 offset:2240
	ds_write_b16_d16_hi v90, v83 offset:2368
	v_cvt_pk_bf16_f32 v84, v9, v41
	v_cvt_pk_bf16_f32 v85, v25, v57
	ds_write_b16 v90, v84 offset:2448
	ds_write_b16_d16_hi v90, v84 offset:2576
	ds_write_b16 v90, v85 offset:2512
	ds_write_b16_d16_hi v90, v85 offset:2640
	v_cvt_pk_bf16_f32 v82, v10, v42
	v_cvt_pk_bf16_f32 v83, v26, v58
	ds_write_b16 v90, v82 offset:2720
	ds_write_b16_d16_hi v90, v82 offset:2848
	ds_write_b16 v90, v83 offset:2784
	ds_write_b16_d16_hi v90, v83 offset:2912
	v_cvt_pk_bf16_f32 v84, v11, v43
	v_cvt_pk_bf16_f32 v85, v27, v59
	ds_write_b16 v90, v84 offset:2992
	ds_write_b16_d16_hi v90, v84 offset:3120
	ds_write_b16 v90, v85 offset:3056
	ds_write_b16_d16_hi v90, v85 offset:3184
	v_cvt_pk_bf16_f32 v82, v12, v44
	v_cvt_pk_bf16_f32 v83, v28, v60
	ds_write_b16 v90, v82 offset:3264
	ds_write_b16_d16_hi v90, v82 offset:3392
	ds_write_b16 v90, v83 offset:3328
	ds_write_b16_d16_hi v90, v83 offset:3456
	v_cvt_pk_bf16_f32 v84, v13, v45
	v_cvt_pk_bf16_f32 v85, v29, v61
	ds_write_b16 v90, v84 offset:3536
	ds_write_b16_d16_hi v90, v84 offset:3664
	ds_write_b16 v90, v85 offset:3600
	ds_write_b16_d16_hi v90, v85 offset:3728
	v_cvt_pk_bf16_f32 v82, v14, v46
	v_cvt_pk_bf16_f32 v83, v30, v62
	ds_write_b16 v90, v82 offset:3808
	ds_write_b16_d16_hi v90, v82 offset:3936
	ds_write_b16 v90, v83 offset:3872
	ds_write_b16_d16_hi v90, v83 offset:4000
	v_cvt_pk_bf16_f32 v84, v15, v47
	v_cvt_pk_bf16_f32 v85, v31, v63
	ds_write_b16 v90, v84 offset:4080
	ds_write_b16_d16_hi v90, v84 offset:4208
	ds_write_b16 v90, v85 offset:4144
	ds_write_b16_d16_hi v90, v85 offset:4272
	ds_read_b128 v[0:3], v94
	ds_read_b128 v[4:7], v94 offset:64
	ds_read_b128 v[8:11], v94 offset:128
	ds_read_b128 v[12:15], v94 offset:192
	ds_read_b128 v[16:19], v94 offset:4352
	ds_read_b128 v[20:23], v94 offset:4416
	ds_read_b128 v[24:27], v94 offset:4480
	ds_read_b128 v[28:31], v94 offset:4544
	s_waitcnt lgkmcnt(7)
	v_mfma_f32_16x16x32_bf16 v[32:35], v[102:105], v[0:3], 0
	s_waitcnt lgkmcnt(6)
	v_mfma_f32_16x16x32_bf16 v[32:35], v[110:113], v[4:7], v[32:35]
	s_waitcnt lgkmcnt(5)
	v_mfma_f32_16x16x32_bf16 v[32:35], v[118:121], v[8:11], v[32:35]
	s_waitcnt lgkmcnt(4)
	v_mfma_f32_16x16x32_bf16 v[32:35], v[126:129], v[12:15], v[32:35]
	s_waitcnt lgkmcnt(3)
	v_mfma_f32_16x16x32_bf16 v[40:43], v[102:105], v[16:19], 0
	s_waitcnt lgkmcnt(2)
	v_mfma_f32_16x16x32_bf16 v[40:43], v[110:113], v[20:23], v[40:43]
	s_waitcnt lgkmcnt(1)
	v_mfma_f32_16x16x32_bf16 v[40:43], v[118:121], v[24:27], v[40:43]
	s_waitcnt lgkmcnt(0)
	v_mfma_f32_16x16x32_bf16 v[40:43], v[126:129], v[28:31], v[40:43]
	s_add_i32 s30, s30, 32
	s_cmpk_eq_i32 s30, 0x100
	s_waitcnt vmcnt(2)
	v_pk_fma_f32 v[32:33], v[214:215], v[222:223], v[32:33]
	v_pk_fma_f32 v[34:35], v[216:217], v[224:225], v[34:35]
	v_mul_f32_e32 v36, 0x3d372713, v32
	v_mul_f32_e32 v37, 0x3d372713, v33
	v_mul_f32_e32 v38, 0x3d372713, v34
	v_mul_f32_e32 v39, 0x3d372713, v35
	v_mul_f32_e32 v36, v32, v36
	v_mul_f32_e32 v37, v33, v37
	v_mul_f32_e32 v38, v34, v38
	v_mul_f32_e32 v39, v35, v39
	v_fma_f32 v36, v32, v36, v32
	v_fma_f32 v37, v33, v37, v33
	v_fma_f32 v38, v34, v38, v34
	v_fma_f32 v39, v35, v39, v35
	v_mul_f32_e32 v36, 0x3fcc422a, v36
	v_mul_f32_e32 v37, 0x3fcc422a, v37
	v_mul_f32_e32 v38, 0x3fcc422a, v38
	v_mul_f32_e32 v39, 0x3fcc422a, v39
	v_mul_f32_e32 v36, 0xbfb8aa3b, v36
	v_mul_f32_e32 v37, 0xbfb8aa3b, v37
	v_mul_f32_e32 v38, 0xbfb8aa3b, v38
	v_mul_f32_e32 v39, 0xbfb8aa3b, v39
	v_exp_f32_e32 v36, v36
	v_exp_f32_e32 v37, v37
	v_exp_f32_e32 v38, v38
	v_exp_f32_e32 v39, v39
	v_add_f32_e32 v36, 1.0, v36
	v_add_f32_e32 v37, 1.0, v37
	v_add_f32_e32 v38, 1.0, v38
	v_add_f32_e32 v39, 1.0, v39
	v_rcp_f32_e32 v36, v36
	v_rcp_f32_e32 v37, v37
	v_rcp_f32_e32 v38, v38
	v_rcp_f32_e32 v39, v39
	v_mul_f32_e32 v36, v32, v36
	v_mul_f32_e32 v37, v33, v37
	v_mul_f32_e32 v38, v34, v38
	v_mul_f32_e32 v39, v35, v39
	v_cvt_pk_bf16_f32 v32, v36, v37
	v_cvt_pk_bf16_f32 v33, v38, v39
	global_store_dwordx2 v[230:231], v[32:33], off
	v_pk_fma_f32 v[40:41], v[218:219], v[222:223], v[40:41]
	v_pk_fma_f32 v[42:43], v[220:221], v[224:225], v[42:43]
	v_mul_f32_e32 v44, 0x3d372713, v40
	v_mul_f32_e32 v45, 0x3d372713, v41
	v_mul_f32_e32 v46, 0x3d372713, v42
	v_mul_f32_e32 v47, 0x3d372713, v43
	v_mul_f32_e32 v44, v40, v44
	v_mul_f32_e32 v45, v41, v45
	v_mul_f32_e32 v46, v42, v46
	v_mul_f32_e32 v47, v43, v47
	v_fma_f32 v44, v40, v44, v40
	v_fma_f32 v45, v41, v45, v41
	v_fma_f32 v46, v42, v46, v42
	v_fma_f32 v47, v43, v47, v43
	v_mul_f32_e32 v44, 0x3fcc422a, v44
	v_mul_f32_e32 v45, 0x3fcc422a, v45
	v_mul_f32_e32 v46, 0x3fcc422a, v46
	v_mul_f32_e32 v47, 0x3fcc422a, v47
	v_mul_f32_e32 v44, 0xbfb8aa3b, v44
	v_mul_f32_e32 v45, 0xbfb8aa3b, v45
	v_mul_f32_e32 v46, 0xbfb8aa3b, v46
	v_mul_f32_e32 v47, 0xbfb8aa3b, v47
	v_exp_f32_e32 v44, v44
	v_exp_f32_e32 v45, v45
	v_exp_f32_e32 v46, v46
	v_exp_f32_e32 v47, v47
	v_add_f32_e32 v44, 1.0, v44
	v_add_f32_e32 v45, 1.0, v45
	v_add_f32_e32 v46, 1.0, v46
	v_add_f32_e32 v47, 1.0, v47
	v_rcp_f32_e32 v44, v44
	v_rcp_f32_e32 v45, v45
	v_rcp_f32_e32 v46, v46
	v_rcp_f32_e32 v47, v47
	v_mul_f32_e32 v44, v40, v44
	v_mul_f32_e32 v45, v41, v45
	v_mul_f32_e32 v46, v42, v46
	v_mul_f32_e32 v47, v43, v47
	v_cvt_pk_bf16_f32 v40, v44, v45
	v_cvt_pk_bf16_f32 v41, v46, v47
	global_store_dwordx2 v[232:233], v[40:41], off
	s_waitcnt vmcnt(2)
	s_cbranch_scc0 .Ls5b_tile
	v_mov_b32_e32 v164, v66
	v_mov_b32_e32 v162, v67
	v_mov_b32_e32 v165, v68
	v_mov_b32_e32 v163, v69
